# out-projection MERGED stores widened to dwordx4 the same way (8-byte pieces copied, permlane32_swap + permlane16_swap, counted waits re-derived)
# speedup vs baseline: 1.0254x; 1.0078x over previous
; __device__ __forceinline__ u32x2 pk4(f32x4 v) { u32x2 r; r.x = pk_bf16(v[0], v[1]); r.y = pk_bf16(v[2], v[3]); return r; }
; __device__ __forceinline__ f32x4 unpk4(u32x2 v) { return (f32x4){bf_lo(v.x), bf_hi(v.x), bf_lo(v.y), bf_hi(v.y)}; }
; __device__ __forceinline__ void tie4(u32x2 (&d)[4]) { asm volatile("" : "+v"(d[0]), "+v"(d[1]), "+v"(d[2]), "+v"(d[3])); }
;     template <int POS> __device__ __forceinline__ void run(f32x4 (&acc)[2][2][4][2], const Unit& u, const bf16_t* F, int wr, int wc, int fr, int fq) const {
;         const int w4 = wr * 4 + wc, lane = fq * 16 + fr;
;         const u32x2* s0 = (const u32x2*)F + native_slot(u.pm, u.pn, w4, 0, 0, 0, 0, lane);
;         u32x2 ga[2][4];
;         ld4(ga[0], s0); ld4(ga[1], s0 + 256);
; #pragma unroll
;         for (int e = 0; e < 8; ++e) {
;             if (POS < 2) { if (e < 7) asm volatile("s_waitcnt vmcnt(4)" ::: "memory"); else asm volatile("s_waitcnt vmcnt(0)" ::: "memory"); }
;             else { if (e == 0) asm volatile("s_waitcnt vmcnt(4)" ::: "memory"); else if (e < 7) asm volatile("s_waitcnt vmcnt(8)" ::: "memory"); else asm volatile("s_waitcnt vmcnt(4)" ::: "memory"); }
;             tie4(ga[e & 1]);
;             const int ai = e >> 2, m = e & 3;
; #pragma unroll
;             for (int k = 0; k < 4; ++k) { const int bj = k >> 1, n = k & 1;
;                 const f32x4 f = unpk4(ga[e & 1][k]);
;                 if (POS < 2) acc[ai][bj][m][n] *= f;
;                 else *(u32x2*)(MERGED + (size_t)(u.pm * 256 + ai * 128 + wr * 64 + m * 16 + fr) * 1024 + u.pn * 256 + bj * 128 + wc * 32 + n * 16 + fq * 4) = pk4(f * acc[ai][bj][m][n]);
;             }
;             if (e + 2 < 8) ld4(ga[e & 1], s0 + (e + 2) * 256);
;         }
.LBB0_548:
	v_mbcnt_lo_u32_b32 v206, -1, 0
	v_mbcnt_hi_u32_b32 v206, -1, v206
	v_lshrrev_b32_e32 v206, 1, v206
	v_and_b32_e32 v206, 24, v206
	v_mov_b32_e32 v207, 0
	s_cmp_gt_i32 s68, 1
	s_cselect_b64 s[66:67], -1, 0
	s_mov_b64 s[28:29], -1
	s_and_b64 vcc, exec, s[66:67]
	s_cbranch_vccz .LBB0_551
	s_lshl_b32 s4, s64, 2
	s_add_i32 s28, s4, s76
	s_ashr_i32 s29, s28, 31
	s_lshl_b64 s[28:29], s[28:29], 17
	v_lshl_add_u64 v[144:145], v[134:135], 0, s[28:29]
	global_load_dwordx2 v[142:143], v[144:145], off nt
	global_load_dwordx2 v[152:153], v[144:145], off offset:512 nt
	global_load_dwordx2 v[154:155], v[144:145], off offset:1024 nt
	global_load_dwordx2 v[156:157], v[144:145], off offset:1536 nt
	v_lshl_add_u64 v[158:159], v[144:145], 0, s[20:21]
	global_load_dwordx2 v[160:161], v[158:159], off nt
	global_load_dwordx2 v[162:163], v[158:159], off offset:512 nt
	global_load_dwordx2 v[164:165], v[158:159], off offset:1024 nt
	global_load_dwordx2 v[158:159], v[158:159], off offset:1536 nt
	s_waitcnt vmcnt(4)
	s_lshl_b32 s4, s64, 8
	v_lshlrev_b32_e32 v166, 16, v142
	v_and_b32_e32 v167, 0xffff0000, v142
	v_lshlrev_b32_e32 v142, 16, v143
	v_and_b32_e32 v143, 0xffff0000, v143
	v_pk_mul_f32 v[142:143], v[126:127], v[142:143]
	v_pk_mul_f32 v[166:167], v[124:125], v[166:167]
	s_lshl_b32 s28, s76, 8
	v_cvt_pk_bf16_f32 v166, v166, v167
	v_cvt_pk_bf16_f32 v167, v142, v143
	v_add_u32_e32 v142, s4, v146
	v_ashrrev_i32_e32 v143, 31, v142
	v_lshlrev_b64 v[168:169], 11, v[142:143]
	s_ashr_i32 s29, s28, 31
	v_lshl_add_u64 v[168:169], s[14:15], 0, v[168:169]
	s_lshl_b64 s[28:29], s[28:29], 1
	v_lshl_add_u64 v[168:169], v[168:169], 0, s[28:29]
	s_mov_b32 s39, s5
	v_lshl_add_u64 v[168:169], v[168:169], 0, s[38:39]
	v_mov_b32_e32 v141, v133
	v_lshl_add_u64 v[168:169], v[168:169], 0, v[140:141]
	v_mov_b32_e32 v172, v166
	v_mov_b32_e32 v173, v167
	v_lshlrev_b32_e32 v166, 16, v152
	v_and_b32_e32 v167, 0xffff0000, v152
	v_lshlrev_b32_e32 v152, 16, v153
	v_and_b32_e32 v153, 0xffff0000, v153
	v_pk_mul_f32 v[152:153], v[122:123], v[152:153]
	v_pk_mul_f32 v[166:167], v[120:121], v[166:167]
	s_nop 0
	v_cvt_pk_bf16_f32 v166, v166, v167
	v_cvt_pk_bf16_f32 v167, v152, v153
	v_lshlrev_b32_e32 v152, 16, v154
	v_and_b32_e32 v153, 0xffff0000, v154
	v_lshlrev_b32_e32 v154, 16, v155
	v_and_b32_e32 v155, 0xffff0000, v155
	v_pk_mul_f32 v[154:155], v[94:95], v[154:155]
	v_pk_mul_f32 v[152:153], v[92:93], v[152:153]
	v_mov_b32_e32 v174, v166
	v_mov_b32_e32 v175, v167
	v_cvt_pk_bf16_f32 v152, v152, v153
	v_cvt_pk_bf16_f32 v153, v154, v155
	v_mov_b32_e32 v176, v152
	v_mov_b32_e32 v177, v153
	v_lshlrev_b32_e32 v152, 16, v156
	v_and_b32_e32 v153, 0xffff0000, v156
	v_lshlrev_b32_e32 v154, 16, v157
	v_and_b32_e32 v155, 0xffff0000, v157
	v_pk_mul_f32 v[154:155], v[90:91], v[154:155]
	v_pk_mul_f32 v[152:153], v[88:89], v[152:153]
	s_nop 0
	v_cvt_pk_bf16_f32 v152, v152, v153
	v_cvt_pk_bf16_f32 v153, v154, v155
	v_mov_b32_e32 v178, v152
	v_mov_b32_e32 v179, v153
	s_nop 1
	v_permlane32_swap_b32_e32 v172, v174
	v_permlane32_swap_b32_e32 v173, v175
	v_permlane32_swap_b32_e32 v176, v178
	v_permlane32_swap_b32_e32 v177, v179
	v_permlane16_swap_b32_e32 v172, v174
	v_permlane16_swap_b32_e32 v173, v175
	v_permlane16_swap_b32_e32 v176, v178
	v_permlane16_swap_b32_e32 v177, v179
	v_lshl_add_u64 v[204:205], v[168:169], 0, v[206:207]
	global_store_dwordx4 v[204:205], v[172:175], off
	global_store_dwordx4 v[204:205], v[176:179], off offset:256
	v_lshl_add_u64 v[152:153], v[144:145], 0, s[42:43]
	global_load_dwordx2 v[154:155], v[152:153], off nt
	global_load_dwordx2 v[156:157], v[152:153], off offset:512 nt
	global_load_dwordx2 v[166:167], v[152:153], off offset:1024 nt
	global_load_dwordx2 v[152:153], v[152:153], off offset:1536 nt
	s_waitcnt vmcnt(6)
	s_nop 0
	v_lshlrev_b32_e32 v168, 16, v160
	v_and_b32_e32 v169, 0xffff0000, v160
	v_lshlrev_b32_e32 v160, 16, v161
	v_and_b32_e32 v161, 0xffff0000, v161
	v_pk_mul_f32 v[160:161], v[118:119], v[160:161]
	v_pk_mul_f32 v[168:169], v[116:117], v[168:169]
	s_nop 0
	v_cvt_pk_bf16_f32 v168, v168, v169
	v_cvt_pk_bf16_f32 v169, v160, v161
	v_add_u32_e32 v160, s4, v148
	v_ashrrev_i32_e32 v161, 31, v160
	v_lshlrev_b64 v[160:161], 11, v[160:161]
	v_lshl_add_u64 v[160:161], s[14:15], 0, v[160:161]
	v_lshl_add_u64 v[160:161], v[160:161], 0, s[28:29]
	v_lshl_add_u64 v[160:161], v[160:161], 0, s[38:39]
	v_lshl_add_u64 v[160:161], v[160:161], 0, v[140:141]
	v_mov_b32_e32 v180, v168
	v_mov_b32_e32 v181, v169
	v_lshlrev_b32_e32 v168, 16, v162
	v_and_b32_e32 v169, 0xffff0000, v162
	v_lshlrev_b32_e32 v162, 16, v163
	v_and_b32_e32 v163, 0xffff0000, v163
	v_pk_mul_f32 v[162:163], v[114:115], v[162:163]
	v_pk_mul_f32 v[168:169], v[112:113], v[168:169]
	s_nop 0
	v_cvt_pk_bf16_f32 v168, v168, v169
	v_cvt_pk_bf16_f32 v169, v162, v163
	v_lshlrev_b32_e32 v162, 16, v164
	v_and_b32_e32 v163, 0xffff0000, v164
	v_lshlrev_b32_e32 v164, 16, v165
	v_and_b32_e32 v165, 0xffff0000, v165
	v_pk_mul_f32 v[164:165], v[86:87], v[164:165]
	v_pk_mul_f32 v[162:163], v[84:85], v[162:163]
	v_mov_b32_e32 v182, v168
	v_mov_b32_e32 v183, v169
	v_cvt_pk_bf16_f32 v162, v162, v163
	v_cvt_pk_bf16_f32 v163, v164, v165
	v_mov_b32_e32 v184, v162
	v_mov_b32_e32 v185, v163
	v_lshlrev_b32_e32 v162, 16, v158
	v_and_b32_e32 v163, 0xffff0000, v158
	v_lshlrev_b32_e32 v158, 16, v159
	v_and_b32_e32 v159, 0xffff0000, v159
	v_pk_mul_f32 v[158:159], v[82:83], v[158:159]
	v_pk_mul_f32 v[162:163], v[80:81], v[162:163]
	s_nop 0
	v_cvt_pk_bf16_f32 v162, v162, v163
	v_cvt_pk_bf16_f32 v163, v158, v159
	v_mov_b32_e32 v186, v162
	v_mov_b32_e32 v187, v163
	s_nop 1
	v_permlane32_swap_b32_e32 v180, v182
	v_permlane32_swap_b32_e32 v181, v183
	v_permlane32_swap_b32_e32 v184, v186
	v_permlane32_swap_b32_e32 v185, v187
	v_permlane16_swap_b32_e32 v180, v182
	v_permlane16_swap_b32_e32 v181, v183
	v_permlane16_swap_b32_e32 v184, v186
	v_permlane16_swap_b32_e32 v185, v187
	v_lshl_add_u64 v[204:205], v[160:161], 0, v[206:207]
	global_store_dwordx4 v[204:205], v[180:183], off
	global_store_dwordx4 v[204:205], v[184:187], off offset:256
	v_lshl_add_u64 v[158:159], v[144:145], 0, s[44:45]
	global_load_dwordx2 v[160:161], v[158:159], off nt
	global_load_dwordx2 v[162:163], v[158:159], off offset:512 nt
	global_load_dwordx2 v[164:165], v[158:159], off offset:1024 nt
	global_load_dwordx2 v[158:159], v[158:159], off offset:1536 nt
	s_waitcnt vmcnt(6)
; __device__ __forceinline__ u32x2 pk4(f32x4 v) { u32x2 r; r.x = pk_bf16(v[0], v[1]); r.y = pk_bf16(v[2], v[3]); return r; }
; __device__ __forceinline__ f32x4 unpk4(u32x2 v) { return (f32x4){bf_lo(v.x), bf_hi(v.x), bf_lo(v.y), bf_hi(v.y)}; }
; __device__ __forceinline__ void tie4(u32x2 (&d)[4]) { asm volatile("" : "+v"(d[0]), "+v"(d[1]), "+v"(d[2]), "+v"(d[3])); }
;     template <int POS> __device__ __forceinline__ void run(f32x4 (&acc)[2][2][4][2], const Unit& u, const bf16_t* F, int wr, int wc, int fr, int fq) const {
;     ...
; #pragma unroll
;         for (int e = 0; e < 8; ++e) {
;             if (POS < 2) { if (e < 7) asm volatile("s_waitcnt vmcnt(4)" ::: "memory"); else asm volatile("s_waitcnt vmcnt(0)" ::: "memory"); }
;             else { if (e == 0) asm volatile("s_waitcnt vmcnt(4)" ::: "memory"); else if (e < 7) asm volatile("s_waitcnt vmcnt(8)" ::: "memory"); else asm volatile("s_waitcnt vmcnt(4)" ::: "memory"); }
;             tie4(ga[e & 1]);
;             const int ai = e >> 2, m = e & 3;
; #pragma unroll
;             for (int k = 0; k < 4; ++k) { const int bj = k >> 1, n = k & 1;
;                 const f32x4 f = unpk4(ga[e & 1][k]);
;                 if (POS < 2) acc[ai][bj][m][n] *= f;
;                 else *(u32x2*)(MERGED + (size_t)(u.pm * 256 + ai * 128 + wr * 64 + m * 16 + fr) * 1024 + u.pn * 256 + bj * 128 + wc * 32 + n * 16 + fq * 4) = pk4(f * acc[ai][bj][m][n]);
;             }
;             if (e + 2 < 8) ld4(ga[e & 1], s0 + (e + 2) * 256);
;         }
	s_nop 0
	v_lshlrev_b32_e32 v168, 16, v154
	v_and_b32_e32 v169, 0xffff0000, v154
	v_lshlrev_b32_e32 v154, 16, v155
	v_and_b32_e32 v155, 0xffff0000, v155
	v_pk_mul_f32 v[154:155], v[110:111], v[154:155]
	v_pk_mul_f32 v[168:169], v[108:109], v[168:169]
	s_nop 0
	v_cvt_pk_bf16_f32 v168, v168, v169
	v_cvt_pk_bf16_f32 v169, v154, v155
	v_add_u32_e32 v154, s4, v149
	v_ashrrev_i32_e32 v155, 31, v154
	v_lshlrev_b64 v[154:155], 11, v[154:155]
	v_lshl_add_u64 v[154:155], s[14:15], 0, v[154:155]
	v_lshl_add_u64 v[154:155], v[154:155], 0, s[28:29]
	v_lshl_add_u64 v[154:155], v[154:155], 0, s[38:39]
	v_lshl_add_u64 v[154:155], v[154:155], 0, v[140:141]
	v_mov_b32_e32 v188, v168
	v_mov_b32_e32 v189, v169
	v_lshlrev_b32_e32 v168, 16, v156
	v_and_b32_e32 v169, 0xffff0000, v156
	v_lshlrev_b32_e32 v156, 16, v157
	v_and_b32_e32 v157, 0xffff0000, v157
	v_pk_mul_f32 v[156:157], v[106:107], v[156:157]
	v_pk_mul_f32 v[168:169], v[104:105], v[168:169]
	s_nop 0
	v_cvt_pk_bf16_f32 v168, v168, v169
	v_cvt_pk_bf16_f32 v169, v156, v157
	v_lshlrev_b32_e32 v156, 16, v166
	v_and_b32_e32 v157, 0xffff0000, v166
	v_lshlrev_b32_e32 v166, 16, v167
	v_and_b32_e32 v167, 0xffff0000, v167
	v_pk_mul_f32 v[166:167], v[78:79], v[166:167]
	v_pk_mul_f32 v[156:157], v[76:77], v[156:157]
	v_mov_b32_e32 v190, v168
	v_mov_b32_e32 v191, v169
	v_cvt_pk_bf16_f32 v156, v156, v157
	v_cvt_pk_bf16_f32 v157, v166, v167
	v_mov_b32_e32 v192, v156
	v_mov_b32_e32 v193, v157
	v_lshlrev_b32_e32 v156, 16, v152
	v_and_b32_e32 v157, 0xffff0000, v152
	v_lshlrev_b32_e32 v152, 16, v153
	v_and_b32_e32 v153, 0xffff0000, v153
	v_pk_mul_f32 v[152:153], v[74:75], v[152:153]
	v_pk_mul_f32 v[156:157], v[72:73], v[156:157]
	s_nop 0
	v_cvt_pk_bf16_f32 v156, v156, v157
	v_cvt_pk_bf16_f32 v157, v152, v153
	v_mov_b32_e32 v194, v156
	v_mov_b32_e32 v195, v157
	s_nop 1
	v_permlane32_swap_b32_e32 v188, v190
	v_permlane32_swap_b32_e32 v189, v191
	v_permlane32_swap_b32_e32 v192, v194
	v_permlane32_swap_b32_e32 v193, v195
	v_permlane16_swap_b32_e32 v188, v190
	v_permlane16_swap_b32_e32 v189, v191
	v_permlane16_swap_b32_e32 v192, v194
	v_permlane16_swap_b32_e32 v193, v195
	v_lshl_add_u64 v[204:205], v[154:155], 0, v[206:207]
	global_store_dwordx4 v[204:205], v[188:191], off
	global_store_dwordx4 v[204:205], v[192:195], off offset:256
	v_lshl_add_u64 v[152:153], v[144:145], 0, s[46:47]
	global_load_dwordx2 v[154:155], v[152:153], off nt
	global_load_dwordx2 v[156:157], v[152:153], off offset:512 nt
	global_load_dwordx2 v[166:167], v[152:153], off offset:1024 nt
	global_load_dwordx2 v[152:153], v[152:153], off offset:1536 nt
	s_waitcnt vmcnt(6)
	s_nop 0
	v_lshlrev_b32_e32 v168, 16, v160
	v_and_b32_e32 v169, 0xffff0000, v160
	v_lshlrev_b32_e32 v160, 16, v161
	v_and_b32_e32 v161, 0xffff0000, v161
	v_pk_mul_f32 v[160:161], v[102:103], v[160:161]
	v_pk_mul_f32 v[168:169], v[100:101], v[168:169]
	s_nop 0
	v_cvt_pk_bf16_f32 v168, v168, v169
	v_cvt_pk_bf16_f32 v169, v160, v161
	v_add_u32_e32 v160, s4, v150
	v_ashrrev_i32_e32 v161, 31, v160
	v_lshlrev_b64 v[160:161], 11, v[160:161]
	v_lshl_add_u64 v[160:161], s[14:15], 0, v[160:161]
	v_lshl_add_u64 v[160:161], v[160:161], 0, s[28:29]
	v_lshl_add_u64 v[160:161], v[160:161], 0, s[38:39]
	v_lshl_add_u64 v[160:161], v[160:161], 0, v[140:141]
	v_mov_b32_e32 v196, v168
	v_mov_b32_e32 v197, v169
	v_lshlrev_b32_e32 v168, 16, v162
	v_and_b32_e32 v169, 0xffff0000, v162
	v_lshlrev_b32_e32 v162, 16, v163
	v_and_b32_e32 v163, 0xffff0000, v163
	v_pk_mul_f32 v[162:163], v[98:99], v[162:163]
	v_pk_mul_f32 v[168:169], v[96:97], v[168:169]
	s_nop 0
	v_cvt_pk_bf16_f32 v168, v168, v169
	v_cvt_pk_bf16_f32 v169, v162, v163
	v_lshlrev_b32_e32 v162, 16, v164
	v_and_b32_e32 v163, 0xffff0000, v164
	v_lshlrev_b32_e32 v164, 16, v165
	v_and_b32_e32 v165, 0xffff0000, v165
	v_pk_mul_f32 v[164:165], v[70:71], v[164:165]
	v_pk_mul_f32 v[162:163], v[68:69], v[162:163]
	v_mov_b32_e32 v198, v168
	v_mov_b32_e32 v199, v169
	v_cvt_pk_bf16_f32 v162, v162, v163
	v_cvt_pk_bf16_f32 v163, v164, v165
	v_mov_b32_e32 v200, v162
	v_mov_b32_e32 v201, v163
	v_lshlrev_b32_e32 v162, 16, v158
	v_and_b32_e32 v163, 0xffff0000, v158
	v_lshlrev_b32_e32 v158, 16, v159
	v_and_b32_e32 v159, 0xffff0000, v159
	v_pk_mul_f32 v[158:159], v[66:67], v[158:159]
	v_pk_mul_f32 v[162:163], v[64:65], v[162:163]
	s_nop 0
	v_cvt_pk_bf16_f32 v162, v162, v163
	v_cvt_pk_bf16_f32 v163, v158, v159
	v_mov_b32_e32 v202, v162
	v_mov_b32_e32 v203, v163
	s_nop 1
	v_permlane32_swap_b32_e32 v196, v198
	v_permlane32_swap_b32_e32 v197, v199
	v_permlane32_swap_b32_e32 v200, v202
	v_permlane32_swap_b32_e32 v201, v203
	v_permlane16_swap_b32_e32 v196, v198
	v_permlane16_swap_b32_e32 v197, v199
	v_permlane16_swap_b32_e32 v200, v202
	v_permlane16_swap_b32_e32 v201, v203
	v_lshl_add_u64 v[204:205], v[160:161], 0, v[206:207]
	global_store_dwordx4 v[204:205], v[196:199], off
	global_store_dwordx4 v[204:205], v[200:203], off offset:256
	v_lshl_add_u64 v[158:159], v[144:145], 0, s[48:49]
	global_load_dwordx2 v[160:161], v[158:159], off nt
	global_load_dwordx2 v[162:163], v[158:159], off offset:512 nt
	global_load_dwordx2 v[164:165], v[158:159], off offset:1024 nt
	global_load_dwordx2 v[158:159], v[158:159], off offset:1536 nt
	s_waitcnt vmcnt(6)
; __device__ __forceinline__ u32x2 pk4(f32x4 v) { u32x2 r; r.x = pk_bf16(v[0], v[1]); r.y = pk_bf16(v[2], v[3]); return r; }
; __device__ __forceinline__ f32x4 unpk4(u32x2 v) { return (f32x4){bf_lo(v.x), bf_hi(v.x), bf_lo(v.y), bf_hi(v.y)}; }
; __device__ __forceinline__ void tie4(u32x2 (&d)[4]) { asm volatile("" : "+v"(d[0]), "+v"(d[1]), "+v"(d[2]), "+v"(d[3])); }
;     template <int POS> __device__ __forceinline__ void run(f32x4 (&acc)[2][2][4][2], const Unit& u, const bf16_t* F, int wr, int wc, int fr, int fq) const {
;     ...
; #pragma unroll
;         for (int e = 0; e < 8; ++e) {
;             if (POS < 2) { if (e < 7) asm volatile("s_waitcnt vmcnt(4)" ::: "memory"); else asm volatile("s_waitcnt vmcnt(0)" ::: "memory"); }
;             else { if (e == 0) asm volatile("s_waitcnt vmcnt(4)" ::: "memory"); else if (e < 7) asm volatile("s_waitcnt vmcnt(8)" ::: "memory"); else asm volatile("s_waitcnt vmcnt(4)" ::: "memory"); }
;             tie4(ga[e & 1]);
;             const int ai = e >> 2, m = e & 3;
; #pragma unroll
;             for (int k = 0; k < 4; ++k) { const int bj = k >> 1, n = k & 1;
;                 const f32x4 f = unpk4(ga[e & 1][k]);
;                 if (POS < 2) acc[ai][bj][m][n] *= f;
;                 else *(u32x2*)(MERGED + (size_t)(u.pm * 256 + ai * 128 + wr * 64 + m * 16 + fr) * 1024 + u.pn * 256 + bj * 128 + wc * 32 + n * 16 + fq * 4) = pk4(f * acc[ai][bj][m][n]);
;             }
;             if (e + 2 < 8) ld4(ga[e & 1], s0 + (e + 2) * 256);
;         }
	s_nop 0
	v_lshlrev_b32_e32 v168, 16, v154
	v_and_b32_e32 v169, 0xffff0000, v154
	v_lshlrev_b32_e32 v154, 16, v155
	v_and_b32_e32 v155, 0xffff0000, v155
	v_pk_mul_f32 v[154:155], v[62:63], v[154:155]
	v_pk_mul_f32 v[168:169], v[60:61], v[168:169]
	s_nop 0
	v_cvt_pk_bf16_f32 v168, v168, v169
	v_cvt_pk_bf16_f32 v169, v154, v155
	v_add_u32_e32 v154, 0x80, v142
	v_ashrrev_i32_e32 v155, 31, v154
	v_lshlrev_b64 v[154:155], 11, v[154:155]
	v_lshl_add_u64 v[154:155], s[14:15], 0, v[154:155]
	v_lshl_add_u64 v[154:155], v[154:155], 0, s[28:29]
	v_lshl_add_u64 v[154:155], v[154:155], 0, s[38:39]
	v_lshl_add_u64 v[154:155], v[154:155], 0, v[140:141]
	v_mov_b32_e32 v172, v168
	v_mov_b32_e32 v173, v169
	v_lshlrev_b32_e32 v168, 16, v156
	v_and_b32_e32 v169, 0xffff0000, v156
	v_lshlrev_b32_e32 v156, 16, v157
	v_and_b32_e32 v157, 0xffff0000, v157
	v_pk_mul_f32 v[156:157], v[58:59], v[156:157]
	v_pk_mul_f32 v[168:169], v[56:57], v[168:169]
	s_nop 0
	v_cvt_pk_bf16_f32 v168, v168, v169
	v_cvt_pk_bf16_f32 v169, v156, v157
	v_lshlrev_b32_e32 v156, 16, v166
	v_and_b32_e32 v157, 0xffff0000, v166
	v_lshlrev_b32_e32 v166, 16, v167
	v_and_b32_e32 v167, 0xffff0000, v167
	v_pk_mul_f32 v[166:167], v[30:31], v[166:167]
	v_pk_mul_f32 v[156:157], v[28:29], v[156:157]
	v_mov_b32_e32 v174, v168
	v_mov_b32_e32 v175, v169
	v_cvt_pk_bf16_f32 v156, v156, v157
	v_cvt_pk_bf16_f32 v157, v166, v167
	v_mov_b32_e32 v176, v156
	v_mov_b32_e32 v177, v157
	v_lshlrev_b32_e32 v156, 16, v152
	v_and_b32_e32 v157, 0xffff0000, v152
	v_lshlrev_b32_e32 v152, 16, v153
	v_and_b32_e32 v153, 0xffff0000, v153
	v_pk_mul_f32 v[152:153], v[26:27], v[152:153]
	v_pk_mul_f32 v[156:157], v[24:25], v[156:157]
	s_nop 0
	v_cvt_pk_bf16_f32 v156, v156, v157
	v_cvt_pk_bf16_f32 v157, v152, v153
	v_mov_b32_e32 v178, v156
	v_mov_b32_e32 v179, v157
	s_nop 1
	v_permlane32_swap_b32_e32 v172, v174
	v_permlane32_swap_b32_e32 v173, v175
	v_permlane32_swap_b32_e32 v176, v178
	v_permlane32_swap_b32_e32 v177, v179
	v_permlane16_swap_b32_e32 v172, v174
	v_permlane16_swap_b32_e32 v173, v175
	v_permlane16_swap_b32_e32 v176, v178
	v_permlane16_swap_b32_e32 v177, v179
	v_lshl_add_u64 v[204:205], v[154:155], 0, v[206:207]
	global_store_dwordx4 v[204:205], v[172:175], off
	global_store_dwordx4 v[204:205], v[176:179], off offset:256
	v_lshl_add_u64 v[152:153], v[144:145], 0, s[50:51]
	global_load_dwordx2 v[154:155], v[152:153], off nt
	global_load_dwordx2 v[156:157], v[152:153], off offset:512 nt
	global_load_dwordx2 v[166:167], v[152:153], off offset:1024 nt
	global_load_dwordx2 v[152:153], v[152:153], off offset:1536 nt
	s_waitcnt vmcnt(6)
	v_lshl_add_u64 v[144:145], v[144:145], 0, s[52:53]
	v_lshlrev_b32_e32 v168, 16, v160
	v_and_b32_e32 v169, 0xffff0000, v160
	v_lshlrev_b32_e32 v160, 16, v161
	v_and_b32_e32 v161, 0xffff0000, v161
	v_pk_mul_f32 v[160:161], v[54:55], v[160:161]
	v_pk_mul_f32 v[168:169], v[52:53], v[168:169]
	s_nop 0
	v_cvt_pk_bf16_f32 v168, v168, v169
	v_cvt_pk_bf16_f32 v169, v160, v161
	v_add_u32_e32 v160, 0x90, v142
	v_ashrrev_i32_e32 v161, 31, v160
	v_lshlrev_b64 v[160:161], 11, v[160:161]
	v_lshl_add_u64 v[160:161], s[14:15], 0, v[160:161]
	v_lshl_add_u64 v[160:161], v[160:161], 0, s[28:29]
	v_lshl_add_u64 v[160:161], v[160:161], 0, s[38:39]
	v_lshl_add_u64 v[160:161], v[160:161], 0, v[140:141]
	v_mov_b32_e32 v180, v168
	v_mov_b32_e32 v181, v169
	v_lshlrev_b32_e32 v168, 16, v162
	v_and_b32_e32 v169, 0xffff0000, v162
	v_lshlrev_b32_e32 v162, 16, v163
	v_and_b32_e32 v163, 0xffff0000, v163
	v_pk_mul_f32 v[162:163], v[50:51], v[162:163]
	v_pk_mul_f32 v[168:169], v[48:49], v[168:169]
	s_nop 0
	v_cvt_pk_bf16_f32 v168, v168, v169
	v_cvt_pk_bf16_f32 v169, v162, v163
	v_lshlrev_b32_e32 v162, 16, v164
	v_and_b32_e32 v163, 0xffff0000, v164
	v_lshlrev_b32_e32 v164, 16, v165
	v_and_b32_e32 v165, 0xffff0000, v165
	v_pk_mul_f32 v[164:165], v[22:23], v[164:165]
	v_pk_mul_f32 v[162:163], v[20:21], v[162:163]
	v_mov_b32_e32 v182, v168
	v_mov_b32_e32 v183, v169
	v_cvt_pk_bf16_f32 v162, v162, v163
	v_cvt_pk_bf16_f32 v163, v164, v165
	v_mov_b32_e32 v184, v162
	v_mov_b32_e32 v185, v163
	v_lshlrev_b32_e32 v162, 16, v158
	v_and_b32_e32 v163, 0xffff0000, v158
	v_lshlrev_b32_e32 v158, 16, v159
	v_and_b32_e32 v159, 0xffff0000, v159
	v_pk_mul_f32 v[158:159], v[18:19], v[158:159]
	v_pk_mul_f32 v[162:163], v[16:17], v[162:163]
	s_nop 0
	v_cvt_pk_bf16_f32 v162, v162, v163
	v_cvt_pk_bf16_f32 v163, v158, v159
	v_mov_b32_e32 v186, v162
	v_mov_b32_e32 v187, v163
	s_nop 1
	v_permlane32_swap_b32_e32 v180, v182
	v_permlane32_swap_b32_e32 v181, v183
	v_permlane32_swap_b32_e32 v184, v186
	v_permlane32_swap_b32_e32 v185, v187
	v_permlane16_swap_b32_e32 v180, v182
	v_permlane16_swap_b32_e32 v181, v183
	v_permlane16_swap_b32_e32 v184, v186
	v_permlane16_swap_b32_e32 v185, v187
	v_lshl_add_u64 v[204:205], v[160:161], 0, v[206:207]
	global_store_dwordx4 v[204:205], v[180:183], off
	global_store_dwordx4 v[204:205], v[184:187], off offset:256
	global_load_dwordx2 v[158:159], v[144:145], off nt
	global_load_dwordx2 v[160:161], v[144:145], off offset:512 nt
	global_load_dwordx2 v[162:163], v[144:145], off offset:1024 nt
	global_load_dwordx2 v[144:145], v[144:145], off offset:1536 nt
	s_waitcnt vmcnt(6)
; __device__ __forceinline__ u32x2 pk4(f32x4 v) { u32x2 r; r.x = pk_bf16(v[0], v[1]); r.y = pk_bf16(v[2], v[3]); return r; }
; __device__ __forceinline__ f32x4 unpk4(u32x2 v) { return (f32x4){bf_lo(v.x), bf_hi(v.x), bf_lo(v.y), bf_hi(v.y)}; }
; __device__ __forceinline__ void tie4(u32x2 (&d)[4]) { asm volatile("" : "+v"(d[0]), "+v"(d[1]), "+v"(d[2]), "+v"(d[3])); }
;     template <int POS> __device__ __forceinline__ void run(f32x4 (&acc)[2][2][4][2], const Unit& u, const bf16_t* F, int wr, int wc, int fr, int fq) const {
;     ...
; #pragma unroll
;         for (int e = 0; e < 8; ++e) {
;             if (POS < 2) { if (e < 7) asm volatile("s_waitcnt vmcnt(4)" ::: "memory"); else asm volatile("s_waitcnt vmcnt(0)" ::: "memory"); }
;             else { if (e == 0) asm volatile("s_waitcnt vmcnt(4)" ::: "memory"); else if (e < 7) asm volatile("s_waitcnt vmcnt(8)" ::: "memory"); else asm volatile("s_waitcnt vmcnt(4)" ::: "memory"); }
;             tie4(ga[e & 1]);
;             const int ai = e >> 2, m = e & 3;
; #pragma unroll
;             for (int k = 0; k < 4; ++k) { const int bj = k >> 1, n = k & 1;
;                 const f32x4 f = unpk4(ga[e & 1][k]);
;                 if (POS < 2) acc[ai][bj][m][n] *= f;
;                 else *(u32x2*)(MERGED + (size_t)(u.pm * 256 + ai * 128 + wr * 64 + m * 16 + fr) * 1024 + u.pn * 256 + bj * 128 + wc * 32 + n * 16 + fq * 4) = pk4(f * acc[ai][bj][m][n]);
;             }
;             if (e + 2 < 8) ld4(ga[e & 1], s0 + (e + 2) * 256);
;         }
	s_nop 0
	v_lshlrev_b32_e32 v164, 16, v154
	v_and_b32_e32 v165, 0xffff0000, v154
	v_lshlrev_b32_e32 v154, 16, v155
	v_and_b32_e32 v155, 0xffff0000, v155
	v_pk_mul_f32 v[154:155], v[46:47], v[154:155]
	v_pk_mul_f32 v[164:165], v[44:45], v[164:165]
	s_nop 0
	v_cvt_pk_bf16_f32 v164, v164, v165
	v_cvt_pk_bf16_f32 v165, v154, v155
	v_add_u32_e32 v154, 0xa0, v142
	v_ashrrev_i32_e32 v155, 31, v154
	v_lshlrev_b64 v[154:155], 11, v[154:155]
	v_lshl_add_u64 v[154:155], s[14:15], 0, v[154:155]
	v_lshl_add_u64 v[154:155], v[154:155], 0, s[28:29]
	v_lshl_add_u64 v[154:155], v[154:155], 0, s[38:39]
	v_lshl_add_u64 v[154:155], v[154:155], 0, v[140:141]
	v_mov_b32_e32 v188, v164
	v_mov_b32_e32 v189, v165
	v_lshlrev_b32_e32 v164, 16, v156
	v_and_b32_e32 v165, 0xffff0000, v156
	v_lshlrev_b32_e32 v156, 16, v157
	v_and_b32_e32 v157, 0xffff0000, v157
	v_pk_mul_f32 v[156:157], v[42:43], v[156:157]
	v_pk_mul_f32 v[164:165], v[40:41], v[164:165]
	v_add_u32_e32 v142, 0xb0, v142
	v_cvt_pk_bf16_f32 v164, v164, v165
	v_cvt_pk_bf16_f32 v165, v156, v157
	v_mov_b32_e32 v190, v164
	v_mov_b32_e32 v191, v165
	v_lshlrev_b32_e32 v156, 16, v166
	v_and_b32_e32 v157, 0xffff0000, v166
	v_lshlrev_b32_e32 v164, 16, v167
	v_and_b32_e32 v165, 0xffff0000, v167
	v_pk_mul_f32 v[164:165], v[14:15], v[164:165]
	v_pk_mul_f32 v[156:157], v[12:13], v[156:157]
	v_ashrrev_i32_e32 v143, 31, v142
	v_cvt_pk_bf16_f32 v156, v156, v157
	v_cvt_pk_bf16_f32 v157, v164, v165
	v_mov_b32_e32 v192, v156
	v_mov_b32_e32 v193, v157
	v_lshlrev_b32_e32 v156, 16, v152
	v_and_b32_e32 v157, 0xffff0000, v152
	v_lshlrev_b32_e32 v152, 16, v153
	v_and_b32_e32 v153, 0xffff0000, v153
	v_pk_mul_f32 v[152:153], v[10:11], v[152:153]
	v_pk_mul_f32 v[156:157], v[8:9], v[156:157]
	v_lshlrev_b64 v[142:143], 11, v[142:143]
	v_cvt_pk_bf16_f32 v156, v156, v157
	v_cvt_pk_bf16_f32 v157, v152, v153
	v_mov_b32_e32 v194, v156
	v_mov_b32_e32 v195, v157
	s_nop 1
	v_permlane32_swap_b32_e32 v188, v190
	v_permlane32_swap_b32_e32 v189, v191
	v_permlane32_swap_b32_e32 v192, v194
	v_permlane32_swap_b32_e32 v193, v195
	v_permlane16_swap_b32_e32 v188, v190
	v_permlane16_swap_b32_e32 v189, v191
	v_permlane16_swap_b32_e32 v192, v194
	v_permlane16_swap_b32_e32 v193, v195
	v_lshl_add_u64 v[204:205], v[154:155], 0, v[206:207]
	global_store_dwordx4 v[204:205], v[188:191], off
	global_store_dwordx4 v[204:205], v[192:195], off offset:256
	v_lshl_add_u64 v[142:143], s[14:15], 0, v[142:143]
	s_waitcnt vmcnt(2)
	v_lshl_add_u64 v[142:143], v[142:143], 0, s[28:29]
	v_lshlrev_b32_e32 v152, 16, v158
	v_and_b32_e32 v153, 0xffff0000, v158
	v_lshlrev_b32_e32 v154, 16, v159
	v_and_b32_e32 v155, 0xffff0000, v159
	v_pk_mul_f32 v[154:155], v[38:39], v[154:155]
	v_pk_mul_f32 v[152:153], v[36:37], v[152:153]
	v_lshl_add_u64 v[142:143], v[142:143], 0, s[38:39]
	v_cvt_pk_bf16_f32 v152, v152, v153
	v_cvt_pk_bf16_f32 v153, v154, v155
	v_lshl_add_u64 v[142:143], v[142:143], 0, v[140:141]
	v_mov_b32_e32 v196, v152
	v_mov_b32_e32 v197, v153
	v_lshlrev_b32_e32 v152, 16, v160
	v_and_b32_e32 v153, 0xffff0000, v160
	v_lshlrev_b32_e32 v154, 16, v161
	v_and_b32_e32 v155, 0xffff0000, v161
	v_pk_mul_f32 v[154:155], v[34:35], v[154:155]
	v_pk_mul_f32 v[152:153], v[32:33], v[152:153]
	s_nop 0
	v_cvt_pk_bf16_f32 v152, v152, v153
	v_cvt_pk_bf16_f32 v153, v154, v155
	v_mov_b32_e32 v198, v152
	v_mov_b32_e32 v199, v153
	v_lshlrev_b32_e32 v152, 16, v162
	v_and_b32_e32 v153, 0xffff0000, v162
	v_lshlrev_b32_e32 v154, 16, v163
	v_and_b32_e32 v155, 0xffff0000, v163
	v_pk_mul_f32 v[154:155], v[6:7], v[154:155]
	v_pk_mul_f32 v[152:153], v[4:5], v[152:153]
	s_nop 0
	v_cvt_pk_bf16_f32 v152, v152, v153
	v_cvt_pk_bf16_f32 v153, v154, v155
	v_mov_b32_e32 v200, v152
	v_mov_b32_e32 v201, v153
	v_lshlrev_b32_e32 v152, 16, v144
	v_and_b32_e32 v153, 0xffff0000, v144
	v_lshlrev_b32_e32 v144, 16, v145
	v_and_b32_e32 v145, 0xffff0000, v145
	v_pk_mul_f32 v[144:145], v[2:3], v[144:145]
	v_pk_mul_f32 v[152:153], v[0:1], v[152:153]
	s_nop 0
	v_cvt_pk_bf16_f32 v152, v152, v153
	v_cvt_pk_bf16_f32 v153, v144, v145
	v_mov_b32_e32 v202, v152
	v_mov_b32_e32 v203, v153
	s_nop 1
	v_permlane32_swap_b32_e32 v196, v198
	v_permlane32_swap_b32_e32 v197, v199
	v_permlane32_swap_b32_e32 v200, v202
	v_permlane32_swap_b32_e32 v201, v203
	v_permlane16_swap_b32_e32 v196, v198
	v_permlane16_swap_b32_e32 v197, v199
	v_permlane16_swap_b32_e32 v200, v202
	v_permlane16_swap_b32_e32 v201, v203
	v_lshl_add_u64 v[204:205], v[142:143], 0, v[206:207]
	global_store_dwordx4 v[204:205], v[196:199], off
	global_store_dwordx4 v[204:205], v[200:203], off offset:256
	s_cbranch_execz .LBB0_552
